# P2 FFN weight items pulled from 30 atomic ticket counters (dynamic balance; the 16 out-projection workgroups join after their GEMM)
# speedup vs baseline: 1.0766x; 1.0048x over previous
; #define LAS __attribute__((address_space(3)))
; DI void p2_ffn_weights(const Params& P, lds_t* lds, int GP, int bx, int wave, int lane) {
;     unsigned char* ws = P.ws;
;     LAS float* scr = (LAS float*)(lds + wave * 16384);
;     constexpr int I_UP = (DM / 64) * (FF / 32), I_DN = (FF / 64) * (DM / 32);
;     for (int it = bx * 8 + wave; it < I_UP + I_DN; it += GP * 8) {
;         if (it < I_UP) p0_transpose_item(P.w_up, DM, FF, (bf16_t*)(ws + WS_WUP), P.norm2, false, scr, it, lane);
;         else p0_transpose_item(P.w_down, FF, DM, (bf16_t*)(ws + WS_WDN), nullptr, false, scr, it - I_UP, lane);
;     }
; }
.Lffq_entry:
	v_and_b32_e32 v109, 7, v201
	v_lshlrev_b32_e32 v108, 4, v109
	v_lshlrev_b32_e32 v111, 2, v109
	v_lshrrev_b32_e32 v109, 3, v201
	v_lshlrev_b32_e32 v110, 5, v109
	v_lshlrev_b32_e32 v112, 4, v109
	v_mov_b32_e32 v114, 1
	v_mov_b32_e32 v115, 0
	s_lshr_b32 s27, s2, 3
	s_sub_u32 s28, s77, 14
	s_sub_u32 s28, s2, s28
	s_cmp_ge_u32 s2, s77
	s_cselect_b32 s27, s28, s27
	s_lshl_b32 s28, s27, 8
	s_add_u32 s28, s28, 0x50100
	s_add_u32 s24, s68, s28
	s_addc_u32 s25, s69, 0
	s_mov_b64 exec, 1
	global_atomic_add v113, v115, v114, s[24:25] sc0
	s_mov_b64 exec, -1
	s_waitcnt vmcnt(0)
	v_readfirstlane_b32 s31, v113
.Lffq_top:
	s_mul_i32 s26, s31, 30
	s_add_u32 s26, s26, s27
	s_cmpk_lt_u32 s26, 0x1000
	s_cbranch_scc0 .Lffq_done
	s_mov_b64 exec, 1
	global_atomic_add v113, v115, v114, s[24:25] sc0
	s_mov_b64 exec, -1
	s_cmpk_lt_u32 s26, 0x800
	s_cbranch_scc0 .Lffqx_dn_p
	s_lshr_b32 s28, s26, 7
	s_and_b32 s29, s26, 0x7f
	v_readlane_b32 s4, v255, 4
	v_readlane_b32 s5, v255, 5
	s_lshl_b32 s30, s28, 20
	s_lshl_b32 s0, s29, 7
	s_add_u32 s30, s30, s0
	s_add_u32 s4, s4, s30
	s_addc_u32 s5, s5, 0
	s_lshl_b32 s30, s29, 16
	s_lshl_b32 s0, s28, 7
	s_add_u32 s30, s30, s0
	s_add_u32 s30, s30, 0xa00000
	s_add_u32 s6, s68, s30
	s_addc_u32 s7, s69, 0
	s_movk_i32 s8, 0x4000
	s_movk_i32 s9, 0x800
	s_mov_b32 s10, 1
	s_branch .Lffqx_gp_p

; #define LAS __attribute__((address_space(3)))
; DI int lane_id() { return (int)__builtin_amdgcn_mbcnt_hi(~0u, __builtin_amdgcn_mbcnt_lo(~0u, 0u)); }
; DI unsigned pk(float a, float b) { f32x2 v = {a, b}; bf16x2_t r = __builtin_convertvector(v, bf16x2_t); return __builtin_bit_cast(unsigned, r); }
; __device__ __forceinline__ void xcd_barrier(const XcdBarrier& b) {
;     asm volatile("s_waitcnt vmcnt(0)" ::: "memory");
;     __syncthreads();
;     if (b.w0 == 0 && lane_id() == 0) {
;         unsigned* bar = b.bar;
;         __builtin_amdgcn_s_waitcnt(0);
;         unsigned nloc = b.st[0], nx = b.st[1];
;         if (nloc == 0u) { xcd_barrier_complete(bar, b.x, nloc, nx); b.st[0] = nloc; b.st[1] = nx; }
; DI void p0_transpose_item(const float* W, int K, int N, bf16_t* WT, const float* gain, bool is_win, LAS float* scr, int item, int lane) {
;     const int nblk = N / 32, kb = item / nblk, nb = item % nblk, k0 = 64 * kb, n0 = 32 * nb;
;     float cs = 1.f; int prow = n0;
;     if (is_win) { prow = win_perm(n0); if (n0 < 512) cs = 0.125f; else if (n0 >= 1280 && n0 < 1792) cs = 0.08838834764831845f; }
; #pragma unroll 8
;     for (int i = 0; i < 32; ++i) { const int kk = 2 * i + (lane >> 5); float w = __builtin_nontemporal_load(W + (size_t)(k0 + kk) * N + n0 + (lane & 31)) * cs;     if (gain) w *= gain[k0 + kk]; scr[kk * 33 + (lane & 31)] = w; }
;     asm volatile("s_waitcnt lgkmcnt(0)" ::: "memory");
;     const int c = lane & 7;
; #pragma unroll
;     for (int j = 0; j < 4; ++j) { const int n = (lane >> 3) + 8 * j; const LAS float* s = scr + (8 * c) * 33 + n;
;         u32x4 o; o.x = pk(s[0 * 33], s[1 * 33]); o.y = pk(s[2 * 33], s[3 * 33]); o.z = pk(s[4 * 33], s[5 * 33]); o.w = pk(s[6 * 33], s[7 * 33]);
;         *(u32x4*)(WT + (size_t)(prow + n) * K + k0 + 8 * c) = o; }
.Lffqx_gp_p:
	v_readlane_b32 s12, v255, 2
	v_readlane_b32 s13, v255, 3
	s_lshl_b32 s28, s28, 8
	s_add_u32 s12, s12, s28
	s_addc_u32 s13, s13, 0
	s_lshl_b32 s28, s8, 3
	v_mad_u32_u24 v40, v109, s28, v108
	v_add_u32_e32 v41, s8, v40
	v_add_u32_e32 v42, s8, v41
	v_add_u32_e32 v43, s8, v42
	v_add_u32_e32 v44, s8, v43
	v_add_u32_e32 v45, s8, v44
	v_add_u32_e32 v46, s8, v45
	v_add_u32_e32 v47, s8, v46
	s_nop 3
	global_load_dwordx4 v[0:3], v40, s[4:5] nt
	global_load_dwordx4 v[4:7], v41, s[4:5] nt
	global_load_dwordx4 v[8:11], v42, s[4:5] nt
	global_load_dwordx4 v[12:15], v43, s[4:5] nt
	global_load_dwordx4 v[16:19], v44, s[4:5] nt
	global_load_dwordx4 v[20:23], v45, s[4:5] nt
	global_load_dwordx4 v[24:27], v46, s[4:5] nt
	global_load_dwordx4 v[28:31], v47, s[4:5] nt
	global_load_dwordx4 v[32:35], v110, s[12:13]
	global_load_dwordx4 v[36:39], v110, s[12:13] offset:16
	s_waitcnt vmcnt(0)
	v_readfirstlane_b32 s31, v113
	v_mad_u32_u24 v48, v111, s9, v112
	v_add_u32_e32 v49, s9, v48
	v_add_u32_e32 v50, s9, v49
	v_add_u32_e32 v51, s9, v50
	s_cmp_eq_u32 s10, 0
	s_cbranch_scc1 .Lffqx_nog_la
	v_mul_f32_e32 v0, v0, v32
	v_mul_f32_e32 v1, v1, v32
	v_mul_f32_e32 v2, v2, v32
	v_mul_f32_e32 v3, v3, v32
	v_mul_f32_e32 v4, v4, v33
	v_mul_f32_e32 v5, v5, v33
	v_mul_f32_e32 v6, v6, v33
	v_mul_f32_e32 v7, v7, v33
	v_mul_f32_e32 v8, v8, v34
	v_mul_f32_e32 v9, v9, v34
	v_mul_f32_e32 v10, v10, v34
	v_mul_f32_e32 v11, v11, v34
	v_mul_f32_e32 v12, v12, v35
	v_mul_f32_e32 v13, v13, v35
	v_mul_f32_e32 v14, v14, v35
	v_mul_f32_e32 v15, v15, v35
	v_mul_f32_e32 v16, v16, v36
	v_mul_f32_e32 v17, v17, v36
	v_mul_f32_e32 v18, v18, v36
	v_mul_f32_e32 v19, v19, v36
	v_mul_f32_e32 v20, v20, v37
	v_mul_f32_e32 v21, v21, v37
	v_mul_f32_e32 v22, v22, v37
	v_mul_f32_e32 v23, v23, v37
	v_mul_f32_e32 v24, v24, v38
	v_mul_f32_e32 v25, v25, v38
	v_mul_f32_e32 v26, v26, v38
	v_mul_f32_e32 v27, v27, v38
	v_mul_f32_e32 v28, v28, v39
	v_mul_f32_e32 v29, v29, v39
	v_mul_f32_e32 v30, v30, v39
	v_mul_f32_e32 v31, v31, v39
.Lffqx_nog_la:
	v_cvt_pk_bf16_f32 v52, v0, v4
	v_cvt_pk_bf16_f32 v53, v8, v12
	v_cvt_pk_bf16_f32 v54, v16, v20
	v_cvt_pk_bf16_f32 v55, v24, v28
	global_store_dwordx4 v48, v[52:55], s[6:7]
	v_cvt_pk_bf16_f32 v56, v1, v5
	v_cvt_pk_bf16_f32 v57, v9, v13
	v_cvt_pk_bf16_f32 v58, v17, v21
	v_cvt_pk_bf16_f32 v59, v25, v29
	global_store_dwordx4 v49, v[56:59], s[6:7]
	v_cvt_pk_bf16_f32 v60, v2, v6
	v_cvt_pk_bf16_f32 v61, v10, v14
	v_cvt_pk_bf16_f32 v62, v18, v22
	v_cvt_pk_bf16_f32 v63, v26, v30
	global_store_dwordx4 v50, v[60:63], s[6:7]
	v_cvt_pk_bf16_f32 v104, v3, v7
	v_cvt_pk_bf16_f32 v105, v11, v15
	v_cvt_pk_bf16_f32 v106, v19, v23
	v_cvt_pk_bf16_f32 v107, v27, v31
	global_store_dwordx4 v51, v[104:107], s[6:7]
	s_branch .Lffq_top
.Lffq_done:
.LBB0_618:
	s_waitcnt vmcnt(0)
	s_waitcnt vmcnt(0) lgkmcnt(0)
	s_barrier
	s_mov_b64 s[0:1], exec
	v_readlane_b32 s4, v255, 15
	v_readlane_b32 s5, v255, 16
	s_and_b64 s[4:5], s[0:1], s[4:5]
	s_mov_b64 exec, s[4:5]
	s_cbranch_execz .LBB0_670
	s_add_i32 s3, 0, 0x20200
	v_mov_b32_e32 v0, s3
	s_waitcnt vmcnt(0) expcnt(0) lgkmcnt(0)
	ds_read_b32 v2, v0
	s_add_i32 s3, 0, 0x20204
	v_mov_b32_e32 v0, s3
	ds_read_b32 v0, v0
	s_waitcnt lgkmcnt(1)
	v_cmp_ne_u32_e32 vcc, 0, v2
	s_cbranch_vccnz .LBB0_634
	v_readlane_b32 s4, v255, 8
	v_readlane_b32 s5, v255, 9
	s_load_dwordx2 s[8:9], s[4:5], 0x4
	s_add_u32 s4, s68, 0x80200
	s_addc_u32 s5, s69, 0
	s_add_u32 s6, s68, 0x80400
	s_addc_u32 s7, s69, 0
	s_waitcnt lgkmcnt(0)
	s_mul_i32 s3, s8, s96
	s_add_u32 s8, s68, 0x80500
	s_mul_i32 s3, s3, s9
	s_addc_u32 s9, s69, 0
	s_add_u32 s10, s68, 0x80600
	s_addc_u32 s11, s69, 0
	s_add_u32 s12, s68, 0x80700
	s_addc_u32 s13, s69, 0
	s_add_u32 s14, s68, 0x80800
	s_addc_u32 s15, s69, 0
	s_add_u32 s16, s68, 0x80900
	s_addc_u32 s17, s69, 0
	s_add_u32 s18, s68, 0x80a00
	s_addc_u32 s19, s69, 0
	s_add_u32 s20, s68, 0x80b00
	s_addc_u32 s21, s69, 0
	s_add_u32 s22, s68, 0x80c00
	s_addc_u32 s23, s69, 0
	s_add_u32 s24, s68, 0x80d00
	s_addc_u32 s25, s69, 0
	s_add_u32 s26, s68, 0x80e00
	s_addc_u32 s27, s69, 0
	s_add_u32 s28, s68, 0x80f00
	s_addc_u32 s29, s69, 0
	s_add_u32 s30, s68, 0x81000
	s_addc_u32 s31, s69, 0
	s_add_u32 s34, s68, 0x81100
	s_addc_u32 s35, s69, 0
	s_add_u32 s36, s68, 0x81200
	s_addc_u32 s37, s69, 0
	s_add_u32 s38, s68, 0x81300
	s_addc_u32 s39, s69, 0
	s_mov_b32 s46, 1
	v_mov_b32_e32 v16, 0
	s_branch .LBB0_622
